# v62 + grid barrier 3 (scan -> P4) replaced by write-through scan stores + one arrival counter polled at the HGRN2 output pass entry; glu GEMM starts without waiting
# baseline (speedup 1.0000x reference)
; __device__ __forceinline__ unsigned xb_ld(unsigned* p)              { return __hip_atomic_load(p, __ATOMIC_RELAXED, __HIP_MEMORY_SCOPE_AGENT); }
; __device__ __forceinline__ unsigned xb_add(unsigned* p, unsigned v) { return __hip_atomic_fetch_add(p, v, __ATOMIC_RELAXED, __HIP_MEMORY_SCOPE_AGENT); }
; #define SEAM(k) do { if (IN(k) && IN((k) + 1)) { xcd_barrier(bar); xcd_barrier(bar); } } while (0)
; #define SEAM(k) do { } while (0)
; __device__ __forceinline__ void xcd_barrier(const XcdBarrier& b) {
;     asm volatile("s_waitcnt vmcnt(0)" ::: "memory");
;     __syncthreads();
;     if (threadIdx.x == 0) {
;         unsigned* bar = b.bar;
;         __builtin_amdgcn_s_waitcnt(0);
;         unsigned nloc = b.st[0], nx = b.st[1];
;         if (nloc == 0u) { xcd_barrier_complete(bar, b.x, nloc, nx); b.st[0] = nloc; b.st[1] = nx; }
;         const unsigned old = xb_add(&bar[XB_XSUB(b.x)], 1u);
;         const unsigned gen = old / nloc;
;         if (old + 1u == (gen + 1u) * nloc) {
;             __builtin_amdgcn_fence(__ATOMIC_RELEASE, "agent");
;             asm volatile("s_waitcnt vmcnt(0)" ::: "memory");
;             asm volatile("buffer_inv sc1" ::: "memory");
;             const unsigned og = xb_add(&bar[XB_TOP], 1u);
;             const unsigned tg = og / nx;
;             const bool last_top = (og + 1u == (tg + 1u) * nx);
;             if (last_top) (void)__hip_atomic_fetch_add(&bar[XB_TOPGEN], 1u, __ATOMIC_RELAXED, __HIP_MEMORY_SCOPE_AGENT);
;             asm volatile("s_waitcnt vmcnt(0)" ::: "memory");
;             (void)__hip_atomic_fetch_add(&bar[XB_XGEN(b.x)], 1u, __ATOMIC_RELAXED, __HIP_MEMORY_SCOPE_AGENT);
;             if (!last_top) XB_SPIN(xb_ld(&bar[XB_TOPGEN]) == tg, bar);
;         } else {
;             asm volatile("buffer_inv sc1" ::: "memory");
;             { unsigned _sp = 0; for (;;) { const unsigned a_ = xb_ld(&bar[XB_TOPGEN]), c_ = xb_ld(&bar[XB_XGEN(b.x)]); if (a_ != gen && c_ != gen) break; __builtin_amdgcn_s_sleep(1);
;                 if ((++_sp & 255u) == 0u) { if (xb_ld(&bar[XB_TMO])) break; if (_sp > XB_SPIN_CAP) { atomicAdd(&bar[XB_TMO], 1u); break; } } } }
;             asm volatile("s_waitcnt vmcnt(0)" ::: "memory");
;         }
;     }
;     __syncthreads();
; }
; __global__ void __launch_bounds__(NWAVES * 64, 2) mk_fwd(Args args) {
;     ...
;     if (IN(3)) { hg_scan(F, (bf16*)(F.ws + WS_DSC), F.bid, F.G); } SEAM(3);
.LBB0_611:
	v_readlane_b32 s4, v238, 0
	v_readlane_b32 s5, v238, 1
	s_cmp_gt_i32 s5, 4
	s_cselect_b64 s[4:5], -1, 0
	s_and_b64 s[0:1], s[0:1], s[4:5]
	s_andn2_b64 vcc, exec, s[0:1]
	s_cbranch_vccnz .LBB0_667
	s_waitcnt vmcnt(0)
	s_barrier
	s_and_saveexec_b64 s[6:7], s[92:93]
	s_cbranch_execz my_scan_arrived
	v_mov_b32_e32 v2, 0x8400
	v_mov_b32_e32 v3, 1
	global_atomic_add v2, v3, s[50:51]
my_scan_arrived:
	s_or_b64 exec, exec, s[6:7]

; __device__ __forceinline__ void hgC_loop(Frame& F, unsigned* ctr) {
;     ...
;     if (tid == 0) { slot[0] = (int)__hip_atomic_fetch_add(ctr, 1u, __ATOMIC_RELAXED, __HIP_MEMORY_SCOPE_AGENT); slot[1] = (int)__hip_atomic_fetch_add(ctr, 1u, __ATOMIC_RELAXED, __HIP_MEMORY_SCOPE_AGENT); }
;     __syncthreads();
.LBB0_684:
	s_add_u32 s4, s50, 0x8000
	s_addc_u32 s5, s51, 0
	s_waitcnt vmcnt(0)
	s_barrier
	s_and_saveexec_b64 s[0:1], s[92:93]
	s_cbranch_execz .LBB0_690
	v_mov_b32_e32 v2, 0x400
my_scanwait:
	global_load_dword v3, v2, s[4:5] sc1
	s_waitcnt vmcnt(0)
	v_readfirstlane_b32 s3, v3
	s_nop 3
	s_cmp_ge_u32 s3, s52
	s_cbranch_scc1 my_scanwait_done
	s_sleep 1
	s_branch my_scanwait
my_scanwait_done:
	s_mov_b64 s[12:13], exec
	v_mbcnt_lo_u32_b32 v2, s12, 0
	v_mbcnt_hi_u32_b32 v2, s13, v2
	v_cmp_eq_u32_e32 vcc, 0, v2
	s_and_saveexec_b64 s[10:11], vcc
	s_cbranch_execz .LBB0_687
	s_bcnt1_i32_b64 s3, s[12:13]
	v_mov_b32_e32 v3, 0
	v_mov_b32_e32 v4, s3
	global_atomic_add v3, v3, v4, s[4:5] sc0

; __device__ __forceinline__ void hgC_loop(Frame& F, unsigned* ctr) {
;     ...
;     int item = slot[0], nxt = slot[1], par = 0;
;     if (item >= 1024) return;
;     v4u sc[4], qh[2], oi[2]; v2u og[4];
;     ...
;     HGC_FETCH(item);
.LBB0_690:
	s_or_b64 exec, exec, s[0:1]
	v_mov_b32_e32 v55, 0
	s_waitcnt lgkmcnt(0)
	s_barrier
	ds_read_b32 v2, v55 offset:53248
	ds_read_b32 v3, v55 offset:53252
	s_movk_i32 s0, 0x3ff
	s_mov_b32 s11, 0
	s_waitcnt lgkmcnt(1)
	v_cmp_lt_i32_e32 vcc, s0, v2
	v_readfirstlane_b32 s18, v2
	s_waitcnt lgkmcnt(0)
	v_readfirstlane_b32 s17, v3
	s_cbranch_vccnz .LBB0_701
	s_lshl_b32 s0, s96, 3
	v_and_b32_e32 v12, 31, v0
	v_readlane_b32 s20, v238, 25
	s_and_b32 s0, s0, 0x1fffffe0
	s_ashr_i32 s19, s18, 31
	s_bfe_u32 s3, s20, 0x20006
	v_or_b32_e32 v90, s0, v12
	s_lshl_b64 s[0:1], s[18:19], 15
	s_add_u32 s0, s46, s0
	v_lshlrev_b32_e32 v2, 4, v0
	v_or_b32_e32 v6, 0x200, v0
	s_addc_u32 s1, s47, s1
	v_and_b32_e32 v54, 0xf0, v2
	v_lshrrev_b32_e32 v14, 4, v6
	v_lshl_add_u64 v[2:3], s[0:1], 0, v[54:55]
	v_lshlrev_b32_e32 v56, 8, v139
	v_mov_b32_e32 v57, v55
	v_lshlrev_b32_e32 v58, 8, v14
	v_mov_b32_e32 v59, v55
	s_lshl_b64 s[14:15], s[18:19], 14
	v_lshl_add_u64 v[4:5], v[2:3], 0, v[56:57]
	v_lshl_add_u64 v[6:7], v[2:3], 0, v[58:59]
	s_add_u32 s12, s48, 0x1000000
	global_load_dwordx4 v[18:21], v[4:5], off sc1
	global_load_dwordx4 v[22:25], v[6:7], off sc1
	v_or_b32_e32 v6, 0x600, v0
	s_addc_u32 s13, s49, 0
	s_lshl_b32 s10, s18, 4
	s_lshl_b32 s16, s18, 6
	v_lshrrev_b32_e32 v15, 4, v6
	v_or_b32_e32 v60, 0x4000, v56
	v_mov_b32_e32 v61, v55
	v_lshlrev_b32_e32 v62, 8, v15
	v_mov_b32_e32 v63, v55
	s_add_u32 s0, s48, s14
	v_lshl_add_u64 v[4:5], v[2:3], 0, v[60:61]
	v_lshl_add_u64 v[2:3], v[2:3], 0, v[62:63]
	s_addc_u32 s1, s49, s15
	s_and_b32 s10, s10, 0xfffff800
	global_load_dwordx4 v[26:29], v[4:5], off sc1
	global_load_dwordx4 v[30:33], v[2:3], off sc1
	v_lshl_add_u64 v[2:3], s[0:1], 0, v[54:55]
	s_add_u32 s0, s12, s14
	v_lshl_add_u64 v[4:5], v[2:3], 0, v[56:57]
	v_lshl_add_u64 v[2:3], v[2:3], 0, v[58:59]
	s_addc_u32 s1, s13, s15
	s_and_b32 s15, s20, 0xffffffc0
	global_load_dwordx4 v[34:37], v[4:5], off
	global_load_dwordx4 v[38:41], v[2:3], off
	v_or_b32_e32 v2, s15, v154
	v_mov_b32_e32 v3, v55
	s_and_b32 s14, s16, 0x7c0
	v_lshlrev_b64 v[2:3], 5, v[2:3]
	v_lshl_add_u64 v[4:5], s[0:1], 0, v[2:3]
	s_or_b32 s0, s10, s14
	global_load_dwordx4 v[50:53], v[4:5], off offset:16
	global_load_dwordx4 v[6:9], v[4:5], off
	v_add_u32_e32 v4, s0, v90
	v_ashrrev_i32_e32 v5, 31, v4
	v_lshlrev_b64 v[4:5], 12, v[4:5]
	s_lshl_b32 s0, s18, 3
	v_lshl_add_u64 v[4:5], s[56:57], 0, v[4:5]
	s_and_b32 s10, s0, 0x300
	v_lshrrev_b32_e32 v13, 5, v154
	v_lshl_add_u64 v[4:5], v[4:5], 0, s[10:11]
	s_lshl_b32 s10, s3, 6
	v_lshl_add_u64 v[4:5], v[4:5], 0, s[10:11]
	v_lshlrev_b32_e32 v10, 3, v13
	v_mov_b32_e32 v11, v55
	v_lshl_add_u64 v[4:5], v[4:5], 0, v[10:11]
	global_load_dwordx2 v[80:81], v[4:5], off offset:3072
	global_load_dwordx2 v[78:79], v[4:5], off offset:3088
	global_load_dwordx2 v[76:77], v[4:5], off offset:3104
	global_load_dwordx2 v[70:71], v[4:5], off offset:3120
	s_lshl_b32 s10, s3, 5
	s_lshl_b32 s0, s3, 2
	v_or_b32_e32 v10, s10, v12
	s_add_i32 s3, s0, 0
	s_movk_i32 s0, 0x110
	v_mul_u32_u24_e32 v10, 0x110, v10
	v_lshlrev_b32_e32 v11, 4, v13
	v_lshlrev_b32_e32 v4, 2, v13
	v_add3_u32 v91, 0, v10, v11
	v_mul_lo_u32 v10, v90, s0
	v_add3_u32 v92, 0, v10, v11
	v_or_b32_e32 v10, s10, v4
	v_readlane_b32 s68, v238, 29
	v_add_u32_e32 v5, 0, v54
	v_mul_u32_u24_e32 v11, 0x110, v139
	v_mul_u32_u24_e32 v12, 0x110, v14
	v_mul_u32_u24_e32 v13, 0x110, v15
	v_lshl_add_u64 v[64:65], s[46:47], 0, v[54:55]
	v_lshl_add_u64 v[66:67], s[48:49], 0, v[54:55]
	v_lshl_add_u64 v[68:69], s[12:13], 0, v[2:3]
	v_lshlrev_b32_e32 v54, 2, v10
	v_readlane_b32 s70, v238, 31
	v_readlane_b32 s71, v238, 32
	v_mbcnt_lo_u32_b32 v2, -1, 0
	v_cmp_gt_u32_e64 s[0:1], 32, v154
	v_lshlrev_b32_e32 v93, 4, v90
	v_lshl_add_u64 v[72:73], s[70:71], 0, v[54:55]
	global_load_dwordx4 v[198:201], v[72:73], off
	global_load_dwordx4 v[202:205], v[72:73], off offset:32
	global_load_dwordx4 v[206:209], v[72:73], off offset:64
	global_load_dwordx4 v[210:213], v[72:73], off offset:96
	v_add_u32_e32 v94, v5, v11
	v_add_u32_e32 v95, v5, v12
	v_add_u32_e32 v96, v5, v13
	s_lshl_b32 s12, s10, 1
	v_lshlrev_b32_e32 v74, 1, v4
	v_mbcnt_hi_u32_b32 v97, -1, v2
	v_mov_b32_e32 v98, 0x358637bd
	v_lshlrev_b32_e32 v54, 1, v10
	s_mov_b64 s[14:15], 0xc500400
	s_mov_b32 s19, 0xc500000
	v_mov_b32_e32 v99, v55
	v_readlane_b32 s69, v238, 30
	v_readlane_b32 s72, v238, 33
	v_readlane_b32 s73, v238, 34
	v_readlane_b32 s74, v238, 35
	v_readlane_b32 s75, v238, 36
	v_readlane_b32 s76, v238, 37
	v_readlane_b32 s77, v238, 38
	v_readlane_b32 s78, v238, 39
	v_readlane_b32 s79, v238, 40
	v_readlane_b32 s80, v238, 41
	v_readlane_b32 s81, v238, 42
	v_readlane_b32 s82, v238, 43
	v_readlane_b32 s83, v238, 44
	s_branch .LBB0_693

; __device__ __forceinline__ void hgC_loop(Frame& F, unsigned* ctr) {
;     ...
;         acc[0] = bflo(oi[0].x); acc[1] = bfhi(oi[0].x); acc[2] = bflo(oi[0].y); acc[3] = bfhi(oi[0].y); acc[4] = bflo(oi[0].z); acc[5] = bfhi(oi[0].z); acc[6] = bflo(oi[0].w); acc[7] = bfhi(oi[0].w);
;         acc[8] = bflo(oi[1].x); acc[9] = bfhi(oi[1].x); acc[10] = bflo(oi[1].y); acc[11] = bfhi(oi[1].y); acc[12] = bflo(oi[1].z); acc[13] = bfhi(oi[1].z); acc[14] = bflo(oi[1].w); acc[15] = bfhi(oi[1].w);
;         v2u ogc[4];
; #pragma unroll
;         for (int q = 0; q < 4; ++q) ogc[q] = og[q];
;         if (tid == 0) slot[par] = (int)__hip_atomic_fetch_add(ctr, 1u, __ATOMIC_RELAXED, __HIP_MEMORY_SCOPE_AGENT);
;         if (nxt < 1024) HGC_FETCH(nxt);
.LBB0_697:
	s_or_b64 exec, exec, s[20:21]
	s_cmpk_lt_i32 s16, 0x400
	s_cselect_b64 s[22:23], -1, 0
	s_cmpk_gt_i32 s16, 0x3ff
	s_cselect_b64 s[20:21], -1, 0
	s_waitcnt vmcnt(4)
	v_mov_b64_e32 v[48:49], v[8:9]
	v_mov_b64_e32 v[42:43], v[50:51]
	s_and_b64 vcc, exec, s[20:21]
	s_waitcnt vmcnt(0)
	v_mov_b64_e32 v[88:89], v[70:71]
	v_mov_b64_e32 v[86:87], v[76:77]
	v_mov_b64_e32 v[84:85], v[78:79]
	v_mov_b64_e32 v[82:83], v[80:81]
	v_mov_b64_e32 v[46:47], v[6:7]
	v_mov_b64_e32 v[44:45], v[52:53]
	s_cbranch_vccnz .LBB0_699
	s_ashr_i32 s17, s16, 31
	s_lshl_b64 s[24:25], s[16:17], 15
	v_lshl_add_u64 v[2:3], v[64:65], 0, s[24:25]
	v_lshl_add_u64 v[4:5], v[2:3], 0, v[56:57]
	s_lshl_b64 s[26:27], s[16:17], 14
	v_lshl_add_u64 v[10:11], v[2:3], 0, v[58:59]
	global_load_dwordx4 v[18:21], v[4:5], off sc1
	global_load_dwordx4 v[22:25], v[10:11], off sc1
	v_lshl_add_u64 v[4:5], v[2:3], 0, v[60:61]
	v_lshl_add_u64 v[2:3], v[2:3], 0, v[62:63]
	s_lshl_b32 s10, s16, 4
	s_lshl_b32 s13, s16, 6
	global_load_dwordx4 v[26:29], v[4:5], off sc1
	global_load_dwordx4 v[30:33], v[2:3], off sc1
	v_lshl_add_u64 v[2:3], v[66:67], 0, s[26:27]
	s_and_b32 s10, s10, 0xfffff800
	v_lshl_add_u64 v[4:5], v[2:3], 0, v[56:57]
	v_lshl_add_u64 v[2:3], v[2:3], 0, v[58:59]
	s_and_b32 s13, s13, 0x7c0
	global_load_dwordx4 v[34:37], v[4:5], off
	global_load_dwordx4 v[38:41], v[2:3], off
	v_lshl_add_u64 v[2:3], v[68:69], 0, s[26:27]
	s_or_b32 s10, s10, s13
	global_load_dwordx4 v[42:45], v[2:3], off offset:16
	global_load_dwordx4 v[46:49], v[2:3], off
	v_add_u32_e32 v2, s10, v90
	v_ashrrev_i32_e32 v3, 31, v2
	v_lshlrev_b64 v[2:3], 12, v[2:3]
	s_lshl_b32 s10, s16, 3
	v_lshl_add_u64 v[2:3], s[56:57], 0, v[2:3]
	s_and_b32 s10, s10, 0x300
	v_lshl_add_u64 v[2:3], v[2:3], 0, s[10:11]
	s_mov_b32 s13, s11
	v_lshl_add_u64 v[2:3], v[2:3], 0, s[12:13]
	v_mov_b32_e32 v75, v55
	v_lshl_add_u64 v[2:3], v[2:3], 0, v[74:75]
	global_load_dwordx2 v[82:83], v[2:3], off offset:3072
	global_load_dwordx2 v[84:85], v[2:3], off offset:3088
	global_load_dwordx2 v[86:87], v[2:3], off offset:3104
	global_load_dwordx2 v[88:89], v[2:3], off offset:3120
